# merge-phase GEMMs now load tiles HBM->LDS directly (global_load_lds, source-side swizzle), double-buffered 2x32KB LDS stages, one barrier per K-step, sigmoid gates parked in freed VGPRs instead of LDS
# speedup vs baseline: 1.0525x; 1.0175x over previous
.LBB0_75:
	s_andn2_b64 vcc, exec, s[24:25]
	s_cbranch_vccnz .LBB0_104
	s_waitcnt vmcnt(27) lgkmcnt(1)
	v_mov_b32_e32 v32, v184
	s_mov_b32 s24, s87
	s_and_b32 s25, s24, 7
	v_readlane_b32 s0, v236, 16
	s_mul_i32 s25, s25, s0
	s_ashr_i32 s24, s24, 3
	s_add_i32 s96, s25, s24
	v_readlane_b32 s0, v239, 51
	s_cmp_ge_i32 s96, s0
	s_cbranch_scc1 .LBB0_104
	s_ashr_i32 s24, s96, 31
	s_lshr_b32 s24, s24, 26
	s_add_i32 s24, s96, s24
	s_ashr_i32 s25, s24, 6
	s_lshl_b32 s25, s25, 3
	s_and_b32 s26, s96, 7
	s_andn2_b32 s24, s24, 63
	s_or_b32 s28, s25, s26
	s_sub_i32 s24, s96, s24
	s_ashr_i32 s29, s28, 31
	s_ashr_i32 s24, s24, 3
	s_lshl_b64 s[28:29], s[28:29], 18
	s_waitcnt vmcnt(17)
	v_mov_b32_e32 v4, v184
	s_add_u32 s28, s76, s28
	s_addc_u32 s29, s77, s29
	v_ashrrev_i32_e32 v0, 3, v4
	s_ashr_i32 s25, s24, 31
	v_readlane_b32 s0, v239, 18
	v_ashrrev_i32_e32 v1, 31, v0
	s_lshl_b64 s[24:25], s[24:25], 18
	v_readlane_b32 s8, v239, 26
	v_lshlrev_b64 v[0:1], 11, v[0:1]
	v_lshlrev_b32_e32 v5, 4, v4
	v_readlane_b32 s9, v239, 27
	s_add_u32 s24, s8, s24
	v_lshl_add_u64 v[2:3], s[28:29], 0, v[0:1]
	v_and_b32_e32 v176, 0x60, v5
	s_addc_u32 s25, s9, s25
	v_lshl_add_u64 v[2:3], v[2:3], 0, v[176:177]
	v_and_b32_e32 v176, 16, v5
	v_and_b32_e32 v4, 0x70, v5
	s_waitcnt vmcnt(16)
	v_lshl_add_u64 v[12:13], v[2:3], 0, v[176:177]
	v_lshl_add_u64 v[0:1], s[24:25], 0, v[0:1]
	v_mov_b32_e32 v5, v177
	v_lshl_add_u64 v[28:29], v[0:1], 0, v[4:5]
	v_add_co_u32_e32 v4, vcc, s47, v12
	s_mov_b32 m0, -1
	global_load_dwordx4 v[0:3], v[12:13], off
	s_nop 0
	v_addc_co_u32_e32 v5, vcc, 0, v13, vcc
	v_add_co_u32_e32 v8, vcc, s48, v12
	v_and_b32_e32 v33, 15, v32
	s_nop 0
	v_addc_co_u32_e32 v9, vcc, 0, v13, vcc
	v_add_co_u32_e32 v12, vcc, 0x30000, v12
	global_load_dwordx4 v[4:7], v[4:5], off
	s_nop 0
	global_load_dwordx4 v[8:11], v[8:9], off
	v_addc_co_u32_e32 v13, vcc, 0, v13, vcc
	v_add_co_u32_e32 v20, vcc, s47, v28
	global_load_dwordx4 v[12:15], v[12:13], off
	s_waitcnt lgkmcnt(0)
	global_load_dwordx4 v[16:19], v[28:29], off
	v_addc_co_u32_e32 v21, vcc, 0, v29, vcc
	v_add_co_u32_e32 v24, vcc, 0x20000, v28
	v_and_b32_e32 v34, 64, v32
	s_nop 0
	v_addc_co_u32_e32 v25, vcc, 0, v29, vcc
	v_add_co_u32_e32 v28, vcc, 0x30000, v28
	global_load_dwordx4 v[20:23], v[20:21], off
	s_nop 0
	global_load_dwordx4 v[24:27], v[24:25], off
	v_addc_co_u32_e32 v29, vcc, 0, v29, vcc
	global_load_dwordx4 v[28:31], v[28:29], off
	v_lshlrev_b32_e32 v162, 2, v32
	v_ashrrev_i32_e32 v35, 1, v32
	s_movk_i32 s0, 0xffc0
	v_lshrrev_b32_e32 v32, 2, v32
	v_readlane_b32 s36, v237, 30
	v_and_or_b32 v163, v35, s0, v33
	v_and_or_b32 v164, v32, 12, v34
	v_readlane_b32 s44, v237, 38
	v_readlane_b32 s45, v237, 39
	v_readlane_b32 s1, v239, 19
	v_readlane_b32 s2, v239, 20
	v_readlane_b32 s3, v239, 21
	v_readlane_b32 s4, v239, 22
	v_readlane_b32 s5, v239, 23
	v_readlane_b32 s6, v239, 24
	v_readlane_b32 s7, v239, 25
	v_readlane_b32 s10, v239, 28
	v_readlane_b32 s11, v239, 29
	v_readlane_b32 s12, v239, 30
	v_readlane_b32 s13, v239, 31
	v_readlane_b32 s14, v239, 32
	v_readlane_b32 s15, v239, 33
	v_readlane_b32 s37, v237, 31
	v_readlane_b32 s38, v237, 32
	v_readlane_b32 s39, v237, 33
	v_readlane_b32 s40, v237, 34
	v_readlane_b32 s41, v237, 35
	v_readlane_b32 s42, v237, 36
	v_readlane_b32 s43, v237, 37
	v_readlane_b32 s46, v237, 40
	v_readlane_b32 s47, v237, 41
	v_readlane_b32 s48, v237, 42
	v_readlane_b32 s49, v237, 43
	v_readlane_b32 s50, v237, 44
	v_readlane_b32 s51, v237, 45
	s_branch .LBB0_79

.LBB0_80:
	v_mov_b32_e32 v160, v0
	v_mov_b32_e32 v161, v1
	s_add_i32 s40, s40, 1
	s_cmp_eq_u32 s40, 4
	s_mov_b32 s85, 0x800000
	s_waitcnt lgkmcnt(0)
	v_lshlrev_b32_e32 v166, 16, v160
	v_and_b32_e32 v167, 0xffff0000, v160
	v_pk_fma_f32 v[156:157], v[92:93], v[166:167], v[156:157]
	v_lshlrev_b32_e32 v92, 16, v161
	v_and_b32_e32 v93, 0xffff0000, v161
	v_pk_fma_f32 v[158:159], v[94:95], v[92:93], v[158:159]
	v_mov_b32_e32 v92, v2
	v_mov_b32_e32 v93, v3
	s_waitcnt lgkmcnt(0)
	v_lshlrev_b32_e32 v94, 16, v92
	v_and_b32_e32 v95, 0xffff0000, v92
	v_pk_fma_f32 v[152:153], v[88:89], v[94:95], v[152:153]
	v_lshlrev_b32_e32 v88, 16, v93
	v_and_b32_e32 v89, 0xffff0000, v93
	v_pk_fma_f32 v[154:155], v[90:91], v[88:89], v[154:155]
	v_mov_b32_e32 v88, v4
	v_mov_b32_e32 v89, v5
	s_waitcnt lgkmcnt(0)
	v_lshlrev_b32_e32 v90, 16, v88
	v_and_b32_e32 v91, 0xffff0000, v88
	v_pk_fma_f32 v[148:149], v[84:85], v[90:91], v[148:149]
	v_lshlrev_b32_e32 v84, 16, v89
	v_and_b32_e32 v85, 0xffff0000, v89
	v_pk_fma_f32 v[150:151], v[86:87], v[84:85], v[150:151]
	v_mov_b32_e32 v84, v6
	v_mov_b32_e32 v85, v7
	s_waitcnt lgkmcnt(0)
	v_lshlrev_b32_e32 v86, 16, v84
	v_and_b32_e32 v87, 0xffff0000, v84
	v_pk_fma_f32 v[144:145], v[80:81], v[86:87], v[144:145]
	v_lshlrev_b32_e32 v80, 16, v85
	v_and_b32_e32 v81, 0xffff0000, v85
	v_pk_fma_f32 v[146:147], v[82:83], v[80:81], v[146:147]
	v_mov_b32_e32 v80, v8
	v_mov_b32_e32 v81, v9
	s_waitcnt lgkmcnt(0)
	v_lshlrev_b32_e32 v82, 16, v80
	v_and_b32_e32 v83, 0xffff0000, v80
	v_pk_fma_f32 v[140:141], v[76:77], v[82:83], v[140:141]
	v_lshlrev_b32_e32 v76, 16, v81
	v_and_b32_e32 v77, 0xffff0000, v81
	v_pk_fma_f32 v[142:143], v[78:79], v[76:77], v[142:143]
	v_mov_b32_e32 v76, v10
	v_mov_b32_e32 v77, v11
	s_waitcnt lgkmcnt(0)
	v_lshlrev_b32_e32 v78, 16, v76
	v_and_b32_e32 v79, 0xffff0000, v76
	v_pk_fma_f32 v[136:137], v[72:73], v[78:79], v[136:137]
	v_lshlrev_b32_e32 v72, 16, v77
	v_and_b32_e32 v73, 0xffff0000, v77
	v_pk_fma_f32 v[138:139], v[74:75], v[72:73], v[138:139]
	v_mov_b32_e32 v72, v12
	v_mov_b32_e32 v73, v13
	s_waitcnt lgkmcnt(0)
	v_lshlrev_b32_e32 v74, 16, v72
	v_and_b32_e32 v75, 0xffff0000, v72
	v_pk_fma_f32 v[132:133], v[68:69], v[74:75], v[132:133]
	v_lshlrev_b32_e32 v68, 16, v73
	v_and_b32_e32 v69, 0xffff0000, v73
	v_pk_fma_f32 v[134:135], v[70:71], v[68:69], v[134:135]
	v_mov_b32_e32 v68, v14
	v_mov_b32_e32 v69, v15
	s_waitcnt lgkmcnt(0)
	v_lshlrev_b32_e32 v70, 16, v68
	v_and_b32_e32 v71, 0xffff0000, v68
	v_pk_fma_f32 v[128:129], v[64:65], v[70:71], v[128:129]
	v_lshlrev_b32_e32 v64, 16, v69
	v_and_b32_e32 v65, 0xffff0000, v69
	v_pk_fma_f32 v[130:131], v[66:67], v[64:65], v[130:131]
	v_mov_b32_e32 v64, v16
	v_mov_b32_e32 v65, v17
	s_waitcnt lgkmcnt(0)
	v_lshlrev_b32_e32 v66, 16, v64
	v_and_b32_e32 v67, 0xffff0000, v64
	v_pk_fma_f32 v[124:125], v[60:61], v[66:67], v[124:125]
	v_lshlrev_b32_e32 v60, 16, v65
	v_and_b32_e32 v61, 0xffff0000, v65
	v_pk_fma_f32 v[126:127], v[62:63], v[60:61], v[126:127]
	v_mov_b32_e32 v60, v18
	v_mov_b32_e32 v61, v19
	s_waitcnt lgkmcnt(0)
	v_lshlrev_b32_e32 v62, 16, v60
	v_and_b32_e32 v63, 0xffff0000, v60
	v_pk_fma_f32 v[120:121], v[56:57], v[62:63], v[120:121]
	v_lshlrev_b32_e32 v56, 16, v61
	v_and_b32_e32 v57, 0xffff0000, v61
	v_pk_fma_f32 v[122:123], v[58:59], v[56:57], v[122:123]
	v_mov_b32_e32 v56, v20
	v_mov_b32_e32 v57, v21
	s_waitcnt lgkmcnt(0)
	v_lshlrev_b32_e32 v58, 16, v56
	v_and_b32_e32 v59, 0xffff0000, v56
	v_pk_fma_f32 v[116:117], v[52:53], v[58:59], v[116:117]
	v_lshlrev_b32_e32 v52, 16, v57
	v_and_b32_e32 v53, 0xffff0000, v57
	v_pk_fma_f32 v[118:119], v[54:55], v[52:53], v[118:119]
	v_mov_b32_e32 v52, v22
	v_mov_b32_e32 v53, v23
	s_waitcnt lgkmcnt(0)
	v_lshlrev_b32_e32 v54, 16, v52
	v_and_b32_e32 v55, 0xffff0000, v52
	v_pk_fma_f32 v[112:113], v[48:49], v[54:55], v[112:113]
	v_lshlrev_b32_e32 v48, 16, v53
	v_and_b32_e32 v49, 0xffff0000, v53
	v_pk_fma_f32 v[114:115], v[50:51], v[48:49], v[114:115]
	v_mov_b32_e32 v48, v24
	v_mov_b32_e32 v49, v25
	s_waitcnt lgkmcnt(0)
	v_lshlrev_b32_e32 v50, 16, v48
	v_and_b32_e32 v51, 0xffff0000, v48
	v_pk_fma_f32 v[108:109], v[44:45], v[50:51], v[108:109]
	v_lshlrev_b32_e32 v44, 16, v49
	v_and_b32_e32 v45, 0xffff0000, v49
	v_pk_fma_f32 v[110:111], v[46:47], v[44:45], v[110:111]
	v_mov_b32_e32 v44, v26
	v_mov_b32_e32 v45, v27
	s_waitcnt lgkmcnt(0)
	v_lshlrev_b32_e32 v46, 16, v44
	v_and_b32_e32 v47, 0xffff0000, v44
	v_pk_fma_f32 v[104:105], v[40:41], v[46:47], v[104:105]
	v_lshlrev_b32_e32 v40, 16, v45
	v_and_b32_e32 v41, 0xffff0000, v45
	v_pk_fma_f32 v[106:107], v[42:43], v[40:41], v[106:107]
	v_mov_b32_e32 v40, v28
	v_mov_b32_e32 v41, v29
	s_waitcnt lgkmcnt(0)
	v_lshlrev_b32_e32 v42, 16, v40
	v_and_b32_e32 v43, 0xffff0000, v40
	v_pk_fma_f32 v[100:101], v[32:33], v[42:43], v[100:101]
	v_lshlrev_b32_e32 v32, 16, v41
	v_and_b32_e32 v33, 0xffff0000, v41
	v_pk_fma_f32 v[102:103], v[34:35], v[32:33], v[102:103]
	v_mov_b32_e32 v32, v30
	v_mov_b32_e32 v33, v31
	s_waitcnt lgkmcnt(0)
	v_lshlrev_b32_e32 v34, 16, v32
	v_and_b32_e32 v35, 0xffff0000, v32
	v_lshlrev_b32_e32 v32, 16, v33
	v_and_b32_e32 v33, 0xffff0000, v33
	v_pk_fma_f32 v[96:97], v[36:37], v[34:35], v[96:97]
	v_pk_fma_f32 v[98:99], v[38:39], v[32:33], v[98:99]
	s_cbranch_scc1 .LBB0_78

.LBB0_84:
	s_cmpk_gt_u32 s41, 0x3bf
	s_cselect_b64 s[92:93], -1, 0
	s_cmp_lg_u32 s41, 0
	s_cbranch_scc1 .Ld_step_1
	v_add_u32_e32 v160, v168, v166
	v_add_u32_e32 v243, v168, v169
	v_add_u32_e32 v241, v167, v166
	v_add_u32_e32 v242, v167, v169
	v_readfirstlane_b32 s100, v184
	s_lshl_b32 s100, s100, 4
	s_cmp_lg_u32 m0, -1
	s_cbranch_scc1 .Ld_step_1
	s_waitcnt vmcnt(0)
	ds_write_b128 v170, v[0:3]
	ds_write_b128 v170, v[4:7] offset:4096
	ds_write_b128 v170, v[8:11] offset:8192
	ds_write_b128 v170, v[12:15] offset:12288
	ds_write_b128 v170, v[16:19] offset:16384
	ds_write_b128 v170, v[20:23] offset:20480
	ds_write_b128 v170, v[24:27] offset:24576
	ds_write_b128 v170, v[28:31] offset:28672
	s_mov_b32 m0, 0
	s_waitcnt lgkmcnt(0)
	s_barrier
.Ld_step_1:
	s_cmpk_gt_u32 s41, 0x3bf
	s_cbranch_scc1 .Ld_last_1
	s_mov_b64 s[86:87], s[38:39]
	s_mov_b64 s[88:89], s[28:29]
	s_mov_b32 s90, 11
	s_mov_b32 s91, 0x10000
	s_add_i32 s98, s41, 64
	s_lshl_b32 s98, s98, 1
	s_branch .Ld_issue_1

.Ld_issue_1:
	v_lshrrev_b32_e32 v244, 3, v184
	v_and_b32_e32 v245, 7, v184
	v_bfe_u32 v246, v184, 4, 3
	v_xor_b32_e32 v245, v245, v246
	v_lshlrev_b32_e32 v244, s90, v244
	v_lshl_add_u32 v244, v245, 4, v244
	v_add_u32_e32 v244, s98, v244
	s_lshr_b32 s101, s41, 6
	s_add_i32 s101, s101, 1
	s_and_b32 s101, s101, 1
	s_lshl_b32 s101, s101, 15
	s_add_u32 s101, s101, s100
	s_mov_b64 s[98:99], s[86:87]
	s_add_u32 m0, s101, 0x0
	s_nop 0
	global_load_lds_dwordx4 v244, s[98:99]
	s_add_u32 s98, s98, s91
	s_addc_u32 s99, s99, 0
	s_add_u32 m0, s101, 0x1000
	s_nop 0
	global_load_lds_dwordx4 v244, s[98:99]
	s_add_u32 s98, s98, s91
	s_addc_u32 s99, s99, 0
	s_add_u32 m0, s101, 0x2000
	s_nop 0
	global_load_lds_dwordx4 v244, s[98:99]
	s_add_u32 s98, s98, s91
	s_addc_u32 s99, s99, 0
	s_add_u32 m0, s101, 0x3000
	s_nop 0
	global_load_lds_dwordx4 v244, s[98:99]
	s_mov_b64 s[98:99], s[88:89]
	s_add_u32 m0, s101, 0x4000
	s_nop 0
	global_load_lds_dwordx4 v244, s[98:99]
	s_add_u32 s98, s98, s91
	s_addc_u32 s99, s99, 0
	s_add_u32 m0, s101, 0x5000
	s_nop 0
	global_load_lds_dwordx4 v244, s[98:99]
	s_add_u32 s98, s98, s91
	s_addc_u32 s99, s99, 0
	s_add_u32 m0, s101, 0x6000
	s_nop 0
	global_load_lds_dwordx4 v244, s[98:99]
	s_add_u32 s98, s98, s91
	s_addc_u32 s99, s99, 0
	s_add_u32 m0, s101, 0x7000
	s_nop 0
	global_load_lds_dwordx4 v244, s[98:99]
.Ld_noissue_1:
	ds_read_b128 v[172:175], v160 offset:16384
	ds_read_b128 v[180:183], v241
	ds_read_b128 v[214:217], v160 offset:18432
	ds_read_b128 v[218:221], v160 offset:20480
	ds_read_b128 v[222:225], v160 offset:22528
	ds_read_b128 v[244:247], v241 offset:2048
	ds_read_b128 v[248:251], v241 offset:4096
	ds_read_b128 v[252:255], v241 offset:6144
	s_waitcnt lgkmcnt(6)
	v_mfma_f32_16x16x32_bf16 v[92:95], v[172:175], v[180:183], v[92:95]
	s_waitcnt lgkmcnt(5)
	v_mfma_f32_16x16x32_bf16 v[88:91], v[214:217], v[180:183], v[88:91]
	s_waitcnt lgkmcnt(4)
	v_mfma_f32_16x16x32_bf16 v[84:87], v[218:221], v[180:183], v[84:87]
	s_waitcnt lgkmcnt(3)
	v_mfma_f32_16x16x32_bf16 v[80:83], v[222:225], v[180:183], v[80:83]
	ds_read_b128 v[180:183], v242
	s_waitcnt lgkmcnt(3)
	v_mfma_f32_16x16x32_bf16 v[76:79], v[172:175], v[244:247], v[76:79]
	v_mfma_f32_16x16x32_bf16 v[72:75], v[214:217], v[244:247], v[72:75]
	v_mfma_f32_16x16x32_bf16 v[68:71], v[218:221], v[244:247], v[68:71]
	v_mfma_f32_16x16x32_bf16 v[64:67], v[222:225], v[244:247], v[64:67]
	ds_read_b128 v[244:247], v242 offset:2048
	s_waitcnt lgkmcnt(3)
	v_mfma_f32_16x16x32_bf16 v[60:63], v[172:175], v[248:251], v[60:63]
	s_waitcnt lgkmcnt(2)
	v_mfma_f32_16x16x32_bf16 v[44:47], v[172:175], v[252:255], v[44:47]
	ds_read_b128 v[172:175], v243 offset:16384
	v_mfma_f32_16x16x32_bf16 v[56:59], v[214:217], v[248:251], v[56:59]
	v_mfma_f32_16x16x32_bf16 v[40:43], v[214:217], v[252:255], v[40:43]
	ds_read_b128 v[214:217], v243 offset:18432
	v_mfma_f32_16x16x32_bf16 v[52:55], v[218:221], v[248:251], v[52:55]
	v_mfma_f32_16x16x32_bf16 v[36:39], v[218:221], v[252:255], v[36:39]
	ds_read_b128 v[218:221], v243 offset:20480
	v_mfma_f32_16x16x32_bf16 v[48:51], v[222:225], v[248:251], v[48:51]
	v_mfma_f32_16x16x32_bf16 v[32:35], v[222:225], v[252:255], v[32:35]
	ds_read_b128 v[222:225], v243 offset:22528
	ds_read_b128 v[248:251], v242 offset:4096
	ds_read_b128 v[252:255], v242 offset:6144
	s_waitcnt lgkmcnt(5)
	v_mfma_f32_16x16x32_bf16 v[92:95], v[172:175], v[180:183], v[92:95]
	v_mfma_f32_16x16x32_bf16 v[76:79], v[172:175], v[244:247], v[76:79]
	s_waitcnt lgkmcnt(4)
	v_mfma_f32_16x16x32_bf16 v[88:91], v[214:217], v[180:183], v[88:91]
	v_mfma_f32_16x16x32_bf16 v[72:75], v[214:217], v[244:247], v[72:75]
	s_waitcnt lgkmcnt(3)
	v_mfma_f32_16x16x32_bf16 v[84:87], v[218:221], v[180:183], v[84:87]
	v_mfma_f32_16x16x32_bf16 v[68:71], v[218:221], v[244:247], v[68:71]
	s_waitcnt lgkmcnt(2)
	v_mfma_f32_16x16x32_bf16 v[80:83], v[222:225], v[180:183], v[80:83]
	v_mfma_f32_16x16x32_bf16 v[64:67], v[222:225], v[244:247], v[64:67]
	s_waitcnt lgkmcnt(1)
	v_mfma_f32_16x16x32_bf16 v[60:63], v[172:175], v[248:251], v[60:63]
	v_mfma_f32_16x16x32_bf16 v[56:59], v[214:217], v[248:251], v[56:59]
	v_mfma_f32_16x16x32_bf16 v[52:55], v[218:221], v[248:251], v[52:55]
	v_mfma_f32_16x16x32_bf16 v[48:51], v[222:225], v[248:251], v[48:51]
	s_waitcnt vmcnt(0)
	s_waitcnt lgkmcnt(0)
	s_barrier
	v_mfma_f32_16x16x32_bf16 v[44:47], v[172:175], v[252:255], v[44:47]
	v_mfma_f32_16x16x32_bf16 v[40:43], v[214:217], v[252:255], v[40:43]
	v_mfma_f32_16x16x32_bf16 v[36:39], v[218:221], v[252:255], v[36:39]
	v_mfma_f32_16x16x32_bf16 v[32:35], v[222:225], v[252:255], v[32:35]
	v_xor_b32_e32 v160, 0x8000, v160
	v_xor_b32_e32 v243, 0x8000, v243
	v_xor_b32_e32 v241, 0x8000, v241
	v_xor_b32_e32 v242, 0x8000, v242
	s_add_i32 s41, s41, 64
	s_andn2_b64 vcc, exec, s[92:93]
	s_cbranch_vccz .LBB0_91
	s_branch .LBB0_84
.LBB0_91:
	v_mul_f32_e32 v92, 0xbfb8aa3b, v92
	v_mul_f32_e32 v93, 0xbfb8aa3b, v93
	v_exp_f32_e32 v92, v92
	v_exp_f32_e32 v93, v93
	v_mul_f32_e32 v88, 0xbfb8aa3b, v88
	v_mul_f32_e32 v89, 0xbfb8aa3b, v89
	v_exp_f32_e32 v88, v88
	v_pk_add_f32 v[92:93], v[92:93], 1.0 op_sel_hi:[1,0]
	v_exp_f32_e32 v89, v89
	v_div_scale_f32 v160, s[28:29], v93, v93, 1.0
	v_rcp_f32_e32 v161, v160
	v_pk_add_f32 v[88:89], v[88:89], 1.0 op_sel_hi:[1,0]
	v_mul_f32_e32 v84, 0xbfb8aa3b, v84
	v_mul_f32_e32 v85, 0xbfb8aa3b, v85
	v_fma_f32 v166, -v160, v161, 1.0
	v_fmac_f32_e32 v161, v166, v161
	v_div_scale_f32 v166, vcc, 1.0, v93, 1.0
	v_mul_f32_e32 v167, v166, v161
	v_fma_f32 v168, -v160, v167, v166
	v_fmac_f32_e32 v167, v168, v161
	v_fma_f32 v160, -v160, v167, v166
	v_div_fmas_f32 v160, v160, v161, v167
	v_div_fixup_f32 v93, v160, v93, 1.0
	v_div_scale_f32 v160, s[28:29], v92, v92, 1.0
	v_rcp_f32_e32 v161, v160
	v_exp_f32_e32 v84, v84
	v_exp_f32_e32 v85, v85
	v_mul_f32_e32 v80, 0xbfb8aa3b, v80
	v_fma_f32 v166, -v160, v161, 1.0
	v_fmac_f32_e32 v161, v166, v161
	v_div_scale_f32 v166, vcc, 1.0, v92, 1.0
	v_mul_f32_e32 v167, v166, v161
	v_fma_f32 v168, -v160, v167, v166
	v_fmac_f32_e32 v167, v168, v161
	v_fma_f32 v160, -v160, v167, v166
	v_div_fmas_f32 v160, v160, v161, v167
	v_div_fixup_f32 v92, v160, v92, 1.0
	v_cvt_pk_bf16_f32 v160, v92, v93
	v_mul_f32_e32 v92, 0xbfb8aa3b, v94
	v_mul_f32_e32 v93, 0xbfb8aa3b, v95
	v_exp_f32_e32 v92, v92
	v_exp_f32_e32 v93, v93
	v_pk_add_f32 v[84:85], v[84:85], 1.0 op_sel_hi:[1,0]
	v_mul_f32_e32 v81, 0xbfb8aa3b, v81
	v_exp_f32_e32 v80, v80
	v_pk_add_f32 v[92:93], v[92:93], 1.0 op_sel_hi:[1,0]
	v_exp_f32_e32 v81, v81
	v_div_scale_f32 v94, s[28:29], v93, v93, 1.0
	v_rcp_f32_e32 v95, v94
	v_pk_add_f32 v[80:81], v[80:81], 1.0 op_sel_hi:[1,0]
	v_mul_f32_e32 v76, 0xbfb8aa3b, v76
	v_mul_f32_e32 v77, 0xbfb8aa3b, v77
	v_fma_f32 v161, -v94, v95, 1.0
	v_fmac_f32_e32 v95, v161, v95
	v_div_scale_f32 v161, vcc, 1.0, v93, 1.0
	v_mul_f32_e32 v166, v161, v95
	v_fma_f32 v167, -v94, v166, v161
	v_fmac_f32_e32 v166, v167, v95
	v_fma_f32 v94, -v94, v166, v161
	v_div_fmas_f32 v94, v94, v95, v166
	v_div_fixup_f32 v93, v94, v93, 1.0
	v_div_scale_f32 v94, s[28:29], v92, v92, 1.0
	v_rcp_f32_e32 v95, v94
	v_exp_f32_e32 v76, v76
	v_exp_f32_e32 v77, v77
	v_mul_f32_e32 v72, 0xbfb8aa3b, v72
	v_fma_f32 v161, -v94, v95, 1.0
	v_fmac_f32_e32 v95, v161, v95
	v_div_scale_f32 v161, vcc, 1.0, v92, 1.0
	v_mul_f32_e32 v166, v161, v95
	v_fma_f32 v167, -v94, v166, v161
	v_fmac_f32_e32 v166, v167, v95
	v_fma_f32 v94, -v94, v166, v161
	v_div_fmas_f32 v94, v94, v95, v166
	v_div_fixup_f32 v92, v94, v92, 1.0
	v_cvt_pk_bf16_f32 v92, v92, v93
	v_mov_b32_e32 v0, v160
	v_mov_b32_e32 v1, v92
	v_div_scale_f32 v92, s[28:29], v89, v89, 1.0
	v_rcp_f32_e32 v93, v92
	v_pk_add_f32 v[76:77], v[76:77], 1.0 op_sel_hi:[1,0]
	v_mul_f32_e32 v73, 0xbfb8aa3b, v73
	v_exp_f32_e32 v72, v72
	v_fma_f32 v94, -v92, v93, 1.0
	v_fmac_f32_e32 v93, v94, v93
	v_div_scale_f32 v94, vcc, 1.0, v89, 1.0
	v_mul_f32_e32 v95, v94, v93
	v_fma_f32 v160, -v92, v95, v94
	v_fmac_f32_e32 v95, v160, v93
	v_fma_f32 v92, -v92, v95, v94
	v_div_fmas_f32 v92, v92, v93, v95
	v_div_fixup_f32 v89, v92, v89, 1.0
	v_div_scale_f32 v92, s[28:29], v88, v88, 1.0
	v_rcp_f32_e32 v93, v92
	v_exp_f32_e32 v73, v73
	v_mul_f32_e32 v68, 0xbfb8aa3b, v68
	v_mul_f32_e32 v69, 0xbfb8aa3b, v69
	v_fma_f32 v94, -v92, v93, 1.0
	v_fmac_f32_e32 v93, v94, v93
	v_div_scale_f32 v94, vcc, 1.0, v88, 1.0
	v_mul_f32_e32 v95, v94, v93
	v_fma_f32 v160, -v92, v95, v94
	v_fmac_f32_e32 v95, v160, v93
	v_fma_f32 v92, -v92, v95, v94
	v_div_fmas_f32 v92, v92, v93, v95
	v_div_fixup_f32 v88, v92, v88, 1.0
	v_cvt_pk_bf16_f32 v92, v88, v89
	v_mul_f32_e32 v88, 0xbfb8aa3b, v90
	v_mul_f32_e32 v89, 0xbfb8aa3b, v91
	v_exp_f32_e32 v88, v88
	v_exp_f32_e32 v89, v89
	v_pk_add_f32 v[72:73], v[72:73], 1.0 op_sel_hi:[1,0]
	v_exp_f32_e32 v68, v68
	v_exp_f32_e32 v69, v69
	v_pk_add_f32 v[88:89], v[88:89], 1.0 op_sel_hi:[1,0]
	v_mul_f32_e32 v64, 0xbfb8aa3b, v64
	v_div_scale_f32 v90, s[28:29], v89, v89, 1.0
	v_rcp_f32_e32 v91, v90
	v_pk_add_f32 v[68:69], v[68:69], 1.0 op_sel_hi:[1,0]
	v_mul_f32_e32 v65, 0xbfb8aa3b, v65
	v_exp_f32_e32 v64, v64
	v_fma_f32 v93, -v90, v91, 1.0
	v_fmac_f32_e32 v91, v93, v91
	v_div_scale_f32 v93, vcc, 1.0, v89, 1.0
	v_mul_f32_e32 v94, v93, v91
	v_fma_f32 v95, -v90, v94, v93
	v_fmac_f32_e32 v94, v95, v91
	v_fma_f32 v90, -v90, v94, v93
	v_div_fmas_f32 v90, v90, v91, v94
	v_div_fixup_f32 v89, v90, v89, 1.0
	v_div_scale_f32 v90, s[28:29], v88, v88, 1.0
	v_rcp_f32_e32 v91, v90
	v_exp_f32_e32 v65, v65
	v_mul_f32_e32 v60, 0xbfb8aa3b, v60
	v_mul_f32_e32 v61, 0xbfb8aa3b, v61
	v_fma_f32 v93, -v90, v91, 1.0
	v_fmac_f32_e32 v91, v93, v91
	v_div_scale_f32 v93, vcc, 1.0, v88, 1.0
	v_mul_f32_e32 v94, v93, v91
	v_fma_f32 v95, -v90, v94, v93
	v_fmac_f32_e32 v94, v95, v91
	v_fma_f32 v90, -v90, v94, v93
	v_div_fmas_f32 v90, v90, v91, v94
	v_div_fixup_f32 v88, v90, v88, 1.0
	v_cvt_pk_bf16_f32 v88, v88, v89
	v_mov_b32_e32 v2, v92
	v_mov_b32_e32 v3, v88
	v_div_scale_f32 v88, s[28:29], v85, v85, 1.0
	v_rcp_f32_e32 v89, v88
	v_pk_add_f32 v[64:65], v[64:65], 1.0 op_sel_hi:[1,0]
	v_exp_f32_e32 v60, v60
	v_exp_f32_e32 v61, v61
	v_fma_f32 v90, -v88, v89, 1.0
	v_fmac_f32_e32 v89, v90, v89
	v_div_scale_f32 v90, vcc, 1.0, v85, 1.0
	v_mul_f32_e32 v91, v90, v89
	v_fma_f32 v92, -v88, v91, v90
	v_fmac_f32_e32 v91, v92, v89
	v_fma_f32 v88, -v88, v91, v90
	v_div_fmas_f32 v88, v88, v89, v91
	v_div_fixup_f32 v85, v88, v85, 1.0
	v_div_scale_f32 v88, s[28:29], v84, v84, 1.0
	v_rcp_f32_e32 v89, v88
	v_pk_add_f32 v[60:61], v[60:61], 1.0 op_sel_hi:[1,0]
	v_mul_f32_e32 v56, 0xbfb8aa3b, v56
	v_mul_f32_e32 v57, 0xbfb8aa3b, v57
	v_fma_f32 v90, -v88, v89, 1.0
	v_fmac_f32_e32 v89, v90, v89
	v_div_scale_f32 v90, vcc, 1.0, v84, 1.0
	v_mul_f32_e32 v91, v90, v89
	v_fma_f32 v92, -v88, v91, v90
	v_fmac_f32_e32 v91, v92, v89
	v_fma_f32 v88, -v88, v91, v90
	v_div_fmas_f32 v88, v88, v89, v91
	v_div_fixup_f32 v84, v88, v84, 1.0
	v_cvt_pk_bf16_f32 v88, v84, v85
	v_mul_f32_e32 v84, 0xbfb8aa3b, v86
	v_mul_f32_e32 v85, 0xbfb8aa3b, v87
	v_exp_f32_e32 v84, v84
	v_exp_f32_e32 v85, v85
	v_exp_f32_e32 v56, v56
	v_exp_f32_e32 v57, v57
	v_mul_f32_e32 v52, 0xbfb8aa3b, v52
	v_pk_add_f32 v[84:85], v[84:85], 1.0 op_sel_hi:[1,0]
	v_mul_f32_e32 v53, 0xbfb8aa3b, v53
	v_div_scale_f32 v86, s[28:29], v85, v85, 1.0
	v_rcp_f32_e32 v87, v86
	v_pk_add_f32 v[56:57], v[56:57], 1.0 op_sel_hi:[1,0]
	v_exp_f32_e32 v52, v52
	v_exp_f32_e32 v53, v53
	v_fma_f32 v89, -v86, v87, 1.0
	v_fmac_f32_e32 v87, v89, v87
	v_div_scale_f32 v89, vcc, 1.0, v85, 1.0
	v_mul_f32_e32 v90, v89, v87
	v_fma_f32 v91, -v86, v90, v89
	v_fmac_f32_e32 v90, v91, v87
	v_fma_f32 v86, -v86, v90, v89
	v_div_fmas_f32 v86, v86, v87, v90
	v_div_fixup_f32 v85, v86, v85, 1.0
	v_div_scale_f32 v86, s[28:29], v84, v84, 1.0
	v_rcp_f32_e32 v87, v86
	v_pk_add_f32 v[52:53], v[52:53], 1.0 op_sel_hi:[1,0]
	v_mul_f32_e32 v48, 0xbfb8aa3b, v48
	v_mul_f32_e32 v49, 0xbfb8aa3b, v49
	v_fma_f32 v89, -v86, v87, 1.0
	v_fmac_f32_e32 v87, v89, v87
	v_div_scale_f32 v89, vcc, 1.0, v84, 1.0
	v_mul_f32_e32 v90, v89, v87
	v_fma_f32 v91, -v86, v90, v89
	v_fmac_f32_e32 v90, v91, v87
	v_fma_f32 v86, -v86, v90, v89
	v_div_fmas_f32 v86, v86, v87, v90
	v_div_fixup_f32 v84, v86, v84, 1.0
	v_cvt_pk_bf16_f32 v84, v84, v85
	v_mov_b32_e32 v4, v88
	v_mov_b32_e32 v5, v84
	v_div_scale_f32 v84, s[28:29], v81, v81, 1.0
	v_rcp_f32_e32 v85, v84
	v_exp_f32_e32 v48, v48
	v_exp_f32_e32 v49, v49
	v_mul_f32_e32 v44, 0xbfb8aa3b, v44
	v_fma_f32 v86, -v84, v85, 1.0
	v_fmac_f32_e32 v85, v86, v85
	v_div_scale_f32 v86, vcc, 1.0, v81, 1.0
	v_mul_f32_e32 v87, v86, v85
	v_fma_f32 v88, -v84, v87, v86
	v_fmac_f32_e32 v87, v88, v85
	v_fma_f32 v84, -v84, v87, v86
	v_div_fmas_f32 v84, v84, v85, v87
	v_div_fixup_f32 v81, v84, v81, 1.0
	v_div_scale_f32 v84, s[28:29], v80, v80, 1.0
	v_rcp_f32_e32 v85, v84
	v_pk_add_f32 v[48:49], v[48:49], 1.0 op_sel_hi:[1,0]
	v_mul_f32_e32 v45, 0xbfb8aa3b, v45
	v_exp_f32_e32 v44, v44
	v_fma_f32 v86, -v84, v85, 1.0
	v_fmac_f32_e32 v85, v86, v85
	v_div_scale_f32 v86, vcc, 1.0, v80, 1.0
	v_mul_f32_e32 v87, v86, v85
	v_fma_f32 v88, -v84, v87, v86
	v_fmac_f32_e32 v87, v88, v85
	v_fma_f32 v84, -v84, v87, v86
	v_div_fmas_f32 v84, v84, v85, v87
	v_div_fixup_f32 v80, v84, v80, 1.0
	v_cvt_pk_bf16_f32 v84, v80, v81
	v_mul_f32_e32 v80, 0xbfb8aa3b, v82
	v_mul_f32_e32 v81, 0xbfb8aa3b, v83
	v_exp_f32_e32 v80, v80
	v_exp_f32_e32 v81, v81
	v_exp_f32_e32 v45, v45
	v_mul_f32_e32 v40, 0xbfb8aa3b, v40
	v_mul_f32_e32 v41, 0xbfb8aa3b, v41
	v_pk_add_f32 v[80:81], v[80:81], 1.0 op_sel_hi:[1,0]
	v_pk_add_f32 v[44:45], v[44:45], 1.0 op_sel_hi:[1,0]
	v_div_scale_f32 v82, s[28:29], v81, v81, 1.0
	v_rcp_f32_e32 v83, v82
	v_exp_f32_e32 v40, v40
	v_exp_f32_e32 v41, v41
	v_mul_f32_e32 v36, 0xbfb8aa3b, v36
	v_fma_f32 v85, -v82, v83, 1.0
	v_fmac_f32_e32 v83, v85, v83
	v_div_scale_f32 v85, vcc, 1.0, v81, 1.0
	v_mul_f32_e32 v86, v85, v83
	v_fma_f32 v87, -v82, v86, v85
	v_fmac_f32_e32 v86, v87, v83
	v_fma_f32 v82, -v82, v86, v85
	v_div_fmas_f32 v82, v82, v83, v86
	v_div_fixup_f32 v81, v82, v81, 1.0
	v_div_scale_f32 v82, s[28:29], v80, v80, 1.0
	v_rcp_f32_e32 v83, v82
	v_pk_add_f32 v[40:41], v[40:41], 1.0 op_sel_hi:[1,0]
	v_mul_f32_e32 v37, 0xbfb8aa3b, v37
	v_exp_f32_e32 v36, v36
	v_fma_f32 v85, -v82, v83, 1.0
	v_fmac_f32_e32 v83, v85, v83
	v_div_scale_f32 v85, vcc, 1.0, v80, 1.0
	v_mul_f32_e32 v86, v85, v83
	v_fma_f32 v87, -v82, v86, v85
	v_fmac_f32_e32 v86, v87, v83
	v_fma_f32 v82, -v82, v86, v85
	v_div_fmas_f32 v82, v82, v83, v86
	v_div_fixup_f32 v80, v82, v80, 1.0
	v_cvt_pk_bf16_f32 v80, v80, v81
	v_mov_b32_e32 v6, v84
	v_mov_b32_e32 v7, v80
	v_div_scale_f32 v80, s[28:29], v77, v77, 1.0
	v_rcp_f32_e32 v81, v80
	v_exp_f32_e32 v37, v37
	v_mul_f32_e32 v32, 0xbfb8aa3b, v32
	v_mul_f32_e32 v33, 0xbfb8aa3b, v33
	v_fma_f32 v82, -v80, v81, 1.0
	v_fmac_f32_e32 v81, v82, v81
	v_div_scale_f32 v82, vcc, 1.0, v77, 1.0
	v_mul_f32_e32 v83, v82, v81
	v_fma_f32 v84, -v80, v83, v82
	v_fmac_f32_e32 v83, v84, v81
	v_fma_f32 v80, -v80, v83, v82
	v_div_fmas_f32 v80, v80, v81, v83
	v_div_fixup_f32 v77, v80, v77, 1.0
	v_div_scale_f32 v80, s[28:29], v76, v76, 1.0
	v_rcp_f32_e32 v81, v80
	v_pk_add_f32 v[36:37], v[36:37], 1.0 op_sel_hi:[1,0]
	v_exp_f32_e32 v32, v32
	v_exp_f32_e32 v33, v33
	v_fma_f32 v82, -v80, v81, 1.0
	v_fmac_f32_e32 v81, v82, v81
	v_div_scale_f32 v82, vcc, 1.0, v76, 1.0
	v_mul_f32_e32 v83, v82, v81
	v_fma_f32 v84, -v80, v83, v82
	v_fmac_f32_e32 v83, v84, v81
	v_fma_f32 v80, -v80, v83, v82
	v_div_fmas_f32 v80, v80, v81, v83
	v_div_fixup_f32 v76, v80, v76, 1.0
	v_cvt_pk_bf16_f32 v80, v76, v77
	v_mul_f32_e32 v76, 0xbfb8aa3b, v78
	v_mul_f32_e32 v77, 0xbfb8aa3b, v79
	v_exp_f32_e32 v76, v76
	v_exp_f32_e32 v77, v77
	v_pk_add_f32 v[32:33], v[32:33], 1.0 op_sel_hi:[1,0]
	s_cmp_eq_u32 s40, 3
	s_mov_b64 s[92:93], s[42:43]
	v_pk_add_f32 v[76:77], v[76:77], 1.0 op_sel_hi:[1,0]
	s_nop 0
	v_div_scale_f32 v78, s[28:29], v77, v77, 1.0
	v_rcp_f32_e32 v79, v78
	s_nop 0
	v_fma_f32 v81, -v78, v79, 1.0
	v_fmac_f32_e32 v79, v81, v79
	v_div_scale_f32 v81, vcc, 1.0, v77, 1.0
	v_mul_f32_e32 v82, v81, v79
	v_fma_f32 v83, -v78, v82, v81
	v_fmac_f32_e32 v82, v83, v79
	v_fma_f32 v78, -v78, v82, v81
	v_div_fmas_f32 v78, v78, v79, v82
	v_div_fixup_f32 v77, v78, v77, 1.0
	v_div_scale_f32 v78, s[28:29], v76, v76, 1.0
	v_rcp_f32_e32 v79, v78
	s_nop 0
	v_fma_f32 v81, -v78, v79, 1.0
	v_fmac_f32_e32 v79, v81, v79
	v_div_scale_f32 v81, vcc, 1.0, v76, 1.0
	v_mul_f32_e32 v82, v81, v79
	v_fma_f32 v83, -v78, v82, v81
	v_fmac_f32_e32 v82, v83, v79
	v_fma_f32 v78, -v78, v82, v81
	v_div_fmas_f32 v78, v78, v79, v82
	v_div_fixup_f32 v76, v78, v76, 1.0
	v_cvt_pk_bf16_f32 v76, v76, v77
	v_mov_b32_e32 v8, v80
	v_mov_b32_e32 v9, v76
	v_div_scale_f32 v76, s[28:29], v73, v73, 1.0
	v_rcp_f32_e32 v77, v76
	s_nop 0
	v_fma_f32 v78, -v76, v77, 1.0
	v_fmac_f32_e32 v77, v78, v77
	v_div_scale_f32 v78, vcc, 1.0, v73, 1.0
	v_mul_f32_e32 v79, v78, v77
	v_fma_f32 v80, -v76, v79, v78
	v_fmac_f32_e32 v79, v80, v77
	v_fma_f32 v76, -v76, v79, v78
	v_div_fmas_f32 v76, v76, v77, v79
	v_div_fixup_f32 v73, v76, v73, 1.0
	v_div_scale_f32 v76, s[28:29], v72, v72, 1.0
	v_rcp_f32_e32 v77, v76
	s_nop 0
	v_fma_f32 v78, -v76, v77, 1.0
	v_fmac_f32_e32 v77, v78, v77
	v_div_scale_f32 v78, vcc, 1.0, v72, 1.0
	v_mul_f32_e32 v79, v78, v77
	v_fma_f32 v80, -v76, v79, v78
	v_fmac_f32_e32 v79, v80, v77
	v_fma_f32 v76, -v76, v79, v78
	v_div_fmas_f32 v76, v76, v77, v79
	v_div_fixup_f32 v72, v76, v72, 1.0
	v_cvt_pk_bf16_f32 v76, v72, v73
	v_mul_f32_e32 v72, 0xbfb8aa3b, v74
	v_mul_f32_e32 v73, 0xbfb8aa3b, v75
	v_exp_f32_e32 v72, v72
	v_exp_f32_e32 v73, v73
	s_nop 0
	v_pk_add_f32 v[72:73], v[72:73], 1.0 op_sel_hi:[1,0]
	s_nop 0
	v_div_scale_f32 v74, s[28:29], v73, v73, 1.0
	v_rcp_f32_e32 v75, v74
	s_nop 0
	v_fma_f32 v77, -v74, v75, 1.0
	v_fmac_f32_e32 v75, v77, v75
	v_div_scale_f32 v77, vcc, 1.0, v73, 1.0
	v_mul_f32_e32 v78, v77, v75
	v_fma_f32 v79, -v74, v78, v77
	v_fmac_f32_e32 v78, v79, v75
	v_fma_f32 v74, -v74, v78, v77
	v_div_fmas_f32 v74, v74, v75, v78
	v_div_fixup_f32 v73, v74, v73, 1.0
	v_div_scale_f32 v74, s[28:29], v72, v72, 1.0
	v_rcp_f32_e32 v75, v74
	s_nop 0
	v_fma_f32 v77, -v74, v75, 1.0
	v_fmac_f32_e32 v75, v77, v75
	v_div_scale_f32 v77, vcc, 1.0, v72, 1.0
	v_mul_f32_e32 v78, v77, v75
	v_fma_f32 v79, -v74, v78, v77
	v_fmac_f32_e32 v78, v79, v75
	v_fma_f32 v74, -v74, v78, v77
	v_div_fmas_f32 v74, v74, v75, v78
	v_div_fixup_f32 v72, v74, v72, 1.0
	v_cvt_pk_bf16_f32 v72, v72, v73
	v_mov_b32_e32 v10, v76
	v_mov_b32_e32 v11, v72
	v_div_scale_f32 v72, s[28:29], v69, v69, 1.0
	v_rcp_f32_e32 v73, v72
	s_nop 0
	v_fma_f32 v74, -v72, v73, 1.0
	v_fmac_f32_e32 v73, v74, v73
	v_div_scale_f32 v74, vcc, 1.0, v69, 1.0
	v_mul_f32_e32 v75, v74, v73
	v_fma_f32 v76, -v72, v75, v74
	v_fmac_f32_e32 v75, v76, v73
	v_fma_f32 v72, -v72, v75, v74
	v_div_fmas_f32 v72, v72, v73, v75
	v_div_fixup_f32 v69, v72, v69, 1.0
	v_div_scale_f32 v72, s[28:29], v68, v68, 1.0
	v_rcp_f32_e32 v73, v72
	s_nop 0
	v_fma_f32 v74, -v72, v73, 1.0
	v_fmac_f32_e32 v73, v74, v73
	v_div_scale_f32 v74, vcc, 1.0, v68, 1.0
	v_mul_f32_e32 v75, v74, v73
	v_fma_f32 v76, -v72, v75, v74
	v_fmac_f32_e32 v75, v76, v73
	v_fma_f32 v72, -v72, v75, v74
	v_div_fmas_f32 v72, v72, v73, v75
	v_div_fixup_f32 v68, v72, v68, 1.0
	v_cvt_pk_bf16_f32 v72, v68, v69
	v_mul_f32_e32 v68, 0xbfb8aa3b, v70
	v_mul_f32_e32 v69, 0xbfb8aa3b, v71
	v_exp_f32_e32 v68, v68
	v_exp_f32_e32 v69, v69
	s_nop 0
	v_pk_add_f32 v[68:69], v[68:69], 1.0 op_sel_hi:[1,0]
	s_nop 0
	v_div_scale_f32 v70, s[28:29], v69, v69, 1.0
	v_rcp_f32_e32 v71, v70
	s_nop 0
	v_fma_f32 v73, -v70, v71, 1.0
	v_fmac_f32_e32 v71, v73, v71
	v_div_scale_f32 v73, vcc, 1.0, v69, 1.0
	v_mul_f32_e32 v74, v73, v71
	v_fma_f32 v75, -v70, v74, v73
	v_fmac_f32_e32 v74, v75, v71
	v_fma_f32 v70, -v70, v74, v73
	v_div_fmas_f32 v70, v70, v71, v74
	v_div_fixup_f32 v69, v70, v69, 1.0
	v_div_scale_f32 v70, s[28:29], v68, v68, 1.0
	v_rcp_f32_e32 v71, v70
	s_nop 0
	v_fma_f32 v73, -v70, v71, 1.0
	v_fmac_f32_e32 v71, v73, v71
	v_div_scale_f32 v73, vcc, 1.0, v68, 1.0
	v_mul_f32_e32 v74, v73, v71
	v_fma_f32 v75, -v70, v74, v73
	v_fmac_f32_e32 v74, v75, v71
	v_fma_f32 v70, -v70, v74, v73
	v_div_fmas_f32 v70, v70, v71, v74
	v_div_fixup_f32 v68, v70, v68, 1.0
	v_cvt_pk_bf16_f32 v68, v68, v69
	v_mov_b32_e32 v12, v72
	v_mov_b32_e32 v13, v68
	v_div_scale_f32 v68, s[28:29], v65, v65, 1.0
	v_rcp_f32_e32 v69, v68
	s_nop 0
	v_fma_f32 v70, -v68, v69, 1.0
	v_fmac_f32_e32 v69, v70, v69
	v_div_scale_f32 v70, vcc, 1.0, v65, 1.0
	v_mul_f32_e32 v71, v70, v69
	v_fma_f32 v72, -v68, v71, v70
	v_fmac_f32_e32 v71, v72, v69
	v_fma_f32 v68, -v68, v71, v70
	v_div_fmas_f32 v68, v68, v69, v71
	v_div_fixup_f32 v65, v68, v65, 1.0
	v_div_scale_f32 v68, s[28:29], v64, v64, 1.0
	v_rcp_f32_e32 v69, v68
	s_nop 0
	v_fma_f32 v70, -v68, v69, 1.0
	v_fmac_f32_e32 v69, v70, v69
	v_div_scale_f32 v70, vcc, 1.0, v64, 1.0
	v_mul_f32_e32 v71, v70, v69
	v_fma_f32 v72, -v68, v71, v70
	v_fmac_f32_e32 v71, v72, v69
	v_fma_f32 v68, -v68, v71, v70
	v_div_fmas_f32 v68, v68, v69, v71
	v_div_fixup_f32 v64, v68, v64, 1.0
	v_cvt_pk_bf16_f32 v68, v64, v65
	v_mul_f32_e32 v64, 0xbfb8aa3b, v66
	v_mul_f32_e32 v65, 0xbfb8aa3b, v67
	v_exp_f32_e32 v64, v64
	v_exp_f32_e32 v65, v65
	s_nop 0
	v_pk_add_f32 v[64:65], v[64:65], 1.0 op_sel_hi:[1,0]
	s_nop 0
	v_div_scale_f32 v66, s[28:29], v65, v65, 1.0
	v_rcp_f32_e32 v67, v66
	s_nop 0
	v_fma_f32 v69, -v66, v67, 1.0
	v_fmac_f32_e32 v67, v69, v67
	v_div_scale_f32 v69, vcc, 1.0, v65, 1.0
	v_mul_f32_e32 v70, v69, v67
	v_fma_f32 v71, -v66, v70, v69
	v_fmac_f32_e32 v70, v71, v67
	v_fma_f32 v66, -v66, v70, v69
	v_div_fmas_f32 v66, v66, v67, v70
	v_div_fixup_f32 v65, v66, v65, 1.0
	v_div_scale_f32 v66, s[28:29], v64, v64, 1.0
	v_rcp_f32_e32 v67, v66
	s_nop 0
	v_fma_f32 v69, -v66, v67, 1.0
	v_fmac_f32_e32 v67, v69, v67
	v_div_scale_f32 v69, vcc, 1.0, v64, 1.0
	v_mul_f32_e32 v70, v69, v67
	v_fma_f32 v71, -v66, v70, v69
	v_fmac_f32_e32 v70, v71, v67
	v_fma_f32 v66, -v66, v70, v69
	v_div_fmas_f32 v66, v66, v67, v70
	v_div_fixup_f32 v64, v66, v64, 1.0
	v_cvt_pk_bf16_f32 v64, v64, v65
	v_mov_b32_e32 v14, v68
	v_mov_b32_e32 v15, v64
	v_div_scale_f32 v64, s[28:29], v61, v61, 1.0
	v_rcp_f32_e32 v65, v64
	s_nop 0
	v_fma_f32 v66, -v64, v65, 1.0
	v_fmac_f32_e32 v65, v66, v65
	v_div_scale_f32 v66, vcc, 1.0, v61, 1.0
	v_mul_f32_e32 v67, v66, v65
	v_fma_f32 v68, -v64, v67, v66
	v_fmac_f32_e32 v67, v68, v65
	v_fma_f32 v64, -v64, v67, v66
	v_div_fmas_f32 v64, v64, v65, v67
	v_div_fixup_f32 v61, v64, v61, 1.0
	v_div_scale_f32 v64, s[28:29], v60, v60, 1.0
	v_rcp_f32_e32 v65, v64
	s_nop 0
	v_fma_f32 v66, -v64, v65, 1.0
	v_fmac_f32_e32 v65, v66, v65
	v_div_scale_f32 v66, vcc, 1.0, v60, 1.0
	v_mul_f32_e32 v67, v66, v65
	v_fma_f32 v68, -v64, v67, v66
	v_fmac_f32_e32 v67, v68, v65
	v_fma_f32 v64, -v64, v67, v66
	v_div_fmas_f32 v64, v64, v65, v67
	v_div_fixup_f32 v60, v64, v60, 1.0
	v_cvt_pk_bf16_f32 v64, v60, v61
	v_mul_f32_e32 v60, 0xbfb8aa3b, v62
	v_mul_f32_e32 v61, 0xbfb8aa3b, v63
	v_exp_f32_e32 v60, v60
	v_exp_f32_e32 v61, v61
	s_nop 0
	v_pk_add_f32 v[60:61], v[60:61], 1.0 op_sel_hi:[1,0]
	s_nop 0
	v_div_scale_f32 v62, s[28:29], v61, v61, 1.0
	v_rcp_f32_e32 v63, v62
	s_nop 0
	v_fma_f32 v65, -v62, v63, 1.0
	v_fmac_f32_e32 v63, v65, v63
	v_div_scale_f32 v65, vcc, 1.0, v61, 1.0
	v_mul_f32_e32 v66, v65, v63
	v_fma_f32 v67, -v62, v66, v65
	v_fmac_f32_e32 v66, v67, v63
	v_fma_f32 v62, -v62, v66, v65
	v_div_fmas_f32 v62, v62, v63, v66
	v_div_fixup_f32 v61, v62, v61, 1.0
	v_div_scale_f32 v62, s[28:29], v60, v60, 1.0
	v_rcp_f32_e32 v63, v62
	s_nop 0
	v_fma_f32 v65, -v62, v63, 1.0
	v_fmac_f32_e32 v63, v65, v63
	v_div_scale_f32 v65, vcc, 1.0, v60, 1.0
	v_mul_f32_e32 v66, v65, v63
	v_fma_f32 v67, -v62, v66, v65
	v_fmac_f32_e32 v66, v67, v63
	v_fma_f32 v62, -v62, v66, v65
	v_div_fmas_f32 v62, v62, v63, v66
	v_div_fixup_f32 v60, v62, v60, 1.0
	v_cvt_pk_bf16_f32 v60, v60, v61
	v_mov_b32_e32 v16, v64
	v_mov_b32_e32 v17, v60
	v_div_scale_f32 v60, s[28:29], v57, v57, 1.0
	v_rcp_f32_e32 v61, v60
	s_nop 0
	v_fma_f32 v62, -v60, v61, 1.0
	v_fmac_f32_e32 v61, v62, v61
	v_div_scale_f32 v62, vcc, 1.0, v57, 1.0
	v_mul_f32_e32 v63, v62, v61
	v_fma_f32 v64, -v60, v63, v62
	v_fmac_f32_e32 v63, v64, v61
	v_fma_f32 v60, -v60, v63, v62
	v_div_fmas_f32 v60, v60, v61, v63
	v_div_fixup_f32 v57, v60, v57, 1.0
	v_div_scale_f32 v60, s[28:29], v56, v56, 1.0
	v_rcp_f32_e32 v61, v60
	s_nop 0
	v_fma_f32 v62, -v60, v61, 1.0
	v_fmac_f32_e32 v61, v62, v61
	v_div_scale_f32 v62, vcc, 1.0, v56, 1.0
	v_mul_f32_e32 v63, v62, v61
	v_fma_f32 v64, -v60, v63, v62
	v_fmac_f32_e32 v63, v64, v61
	v_fma_f32 v60, -v60, v63, v62
	v_div_fmas_f32 v60, v60, v61, v63
	v_div_fixup_f32 v56, v60, v56, 1.0
	v_cvt_pk_bf16_f32 v60, v56, v57
	v_mul_f32_e32 v56, 0xbfb8aa3b, v58
	v_mul_f32_e32 v57, 0xbfb8aa3b, v59
	v_exp_f32_e32 v56, v56
	v_exp_f32_e32 v57, v57
	s_nop 0
	v_pk_add_f32 v[56:57], v[56:57], 1.0 op_sel_hi:[1,0]
	s_nop 0
	v_div_scale_f32 v58, s[28:29], v57, v57, 1.0
	v_rcp_f32_e32 v59, v58
	s_nop 0
	v_fma_f32 v61, -v58, v59, 1.0
	v_fmac_f32_e32 v59, v61, v59
	v_div_scale_f32 v61, vcc, 1.0, v57, 1.0
	v_mul_f32_e32 v62, v61, v59
	v_fma_f32 v63, -v58, v62, v61
	v_fmac_f32_e32 v62, v63, v59
	v_fma_f32 v58, -v58, v62, v61
	v_div_fmas_f32 v58, v58, v59, v62
	v_div_fixup_f32 v57, v58, v57, 1.0
	v_div_scale_f32 v58, s[28:29], v56, v56, 1.0
	v_rcp_f32_e32 v59, v58
	s_nop 0
	v_fma_f32 v61, -v58, v59, 1.0
	v_fmac_f32_e32 v59, v61, v59
	v_div_scale_f32 v61, vcc, 1.0, v56, 1.0
	v_mul_f32_e32 v62, v61, v59
	v_fma_f32 v63, -v58, v62, v61
	v_fmac_f32_e32 v62, v63, v59
	v_fma_f32 v58, -v58, v62, v61
	v_div_fmas_f32 v58, v58, v59, v62
	v_div_fixup_f32 v56, v58, v56, 1.0
	v_cvt_pk_bf16_f32 v56, v56, v57
	v_mov_b32_e32 v18, v60
	v_mov_b32_e32 v19, v56
	v_div_scale_f32 v56, s[28:29], v53, v53, 1.0
	v_rcp_f32_e32 v57, v56
	s_nop 0
	v_fma_f32 v58, -v56, v57, 1.0
	v_fmac_f32_e32 v57, v58, v57
	v_div_scale_f32 v58, vcc, 1.0, v53, 1.0
	v_mul_f32_e32 v59, v58, v57
	v_fma_f32 v60, -v56, v59, v58
	v_fmac_f32_e32 v59, v60, v57
	v_fma_f32 v56, -v56, v59, v58
	v_div_fmas_f32 v56, v56, v57, v59
	v_div_fixup_f32 v53, v56, v53, 1.0
	v_div_scale_f32 v56, s[28:29], v52, v52, 1.0
	v_rcp_f32_e32 v57, v56
	s_nop 0
	v_fma_f32 v58, -v56, v57, 1.0
	v_fmac_f32_e32 v57, v58, v57
	v_div_scale_f32 v58, vcc, 1.0, v52, 1.0
	v_mul_f32_e32 v59, v58, v57
	v_fma_f32 v60, -v56, v59, v58
	v_fmac_f32_e32 v59, v60, v57
	v_fma_f32 v56, -v56, v59, v58
	v_div_fmas_f32 v56, v56, v57, v59
	v_div_fixup_f32 v52, v56, v52, 1.0
	v_cvt_pk_bf16_f32 v56, v52, v53
	v_mul_f32_e32 v52, 0xbfb8aa3b, v54
	v_mul_f32_e32 v53, 0xbfb8aa3b, v55
	v_exp_f32_e32 v52, v52
	v_exp_f32_e32 v53, v53
	s_nop 0
	v_pk_add_f32 v[52:53], v[52:53], 1.0 op_sel_hi:[1,0]
	s_nop 0
	v_div_scale_f32 v54, s[28:29], v53, v53, 1.0
	v_rcp_f32_e32 v55, v54
	s_nop 0
	v_fma_f32 v57, -v54, v55, 1.0
	v_fmac_f32_e32 v55, v57, v55
	v_div_scale_f32 v57, vcc, 1.0, v53, 1.0
	v_mul_f32_e32 v58, v57, v55
	v_fma_f32 v59, -v54, v58, v57
	v_fmac_f32_e32 v58, v59, v55
	v_fma_f32 v54, -v54, v58, v57
	v_div_fmas_f32 v54, v54, v55, v58
	v_div_fixup_f32 v53, v54, v53, 1.0
	v_div_scale_f32 v54, s[28:29], v52, v52, 1.0
	v_rcp_f32_e32 v55, v54
	s_nop 0
	v_fma_f32 v57, -v54, v55, 1.0
	v_fmac_f32_e32 v55, v57, v55
	v_div_scale_f32 v57, vcc, 1.0, v52, 1.0
	v_mul_f32_e32 v58, v57, v55
	v_fma_f32 v59, -v54, v58, v57
	v_fmac_f32_e32 v58, v59, v55
	v_fma_f32 v54, -v54, v58, v57
	v_div_fmas_f32 v54, v54, v55, v58
	v_div_fixup_f32 v52, v54, v52, 1.0
	v_cvt_pk_bf16_f32 v52, v52, v53
	v_mov_b32_e32 v20, v56
	v_mov_b32_e32 v21, v52
	v_div_scale_f32 v52, s[28:29], v49, v49, 1.0
	v_rcp_f32_e32 v53, v52
	s_nop 0
	v_fma_f32 v54, -v52, v53, 1.0
	v_fmac_f32_e32 v53, v54, v53
	v_div_scale_f32 v54, vcc, 1.0, v49, 1.0
	v_mul_f32_e32 v55, v54, v53
	v_fma_f32 v56, -v52, v55, v54
	v_fmac_f32_e32 v55, v56, v53
	v_fma_f32 v52, -v52, v55, v54
	v_div_fmas_f32 v52, v52, v53, v55
	v_div_fixup_f32 v49, v52, v49, 1.0
	v_div_scale_f32 v52, s[28:29], v48, v48, 1.0
	v_rcp_f32_e32 v53, v52
	s_nop 0
	v_fma_f32 v54, -v52, v53, 1.0
	v_fmac_f32_e32 v53, v54, v53
	v_div_scale_f32 v54, vcc, 1.0, v48, 1.0
	v_mul_f32_e32 v55, v54, v53
	v_fma_f32 v56, -v52, v55, v54
	v_fmac_f32_e32 v55, v56, v53
	v_fma_f32 v52, -v52, v55, v54
	v_div_fmas_f32 v52, v52, v53, v55
	v_div_fixup_f32 v48, v52, v48, 1.0
	v_cvt_pk_bf16_f32 v52, v48, v49
	v_mul_f32_e32 v48, 0xbfb8aa3b, v50
	v_mul_f32_e32 v49, 0xbfb8aa3b, v51
	v_exp_f32_e32 v48, v48
	v_exp_f32_e32 v49, v49
	s_nop 0
	v_pk_add_f32 v[48:49], v[48:49], 1.0 op_sel_hi:[1,0]
	s_nop 0
	v_div_scale_f32 v50, s[28:29], v49, v49, 1.0
	v_rcp_f32_e32 v51, v50
	s_nop 0
	v_fma_f32 v53, -v50, v51, 1.0
	v_fmac_f32_e32 v51, v53, v51
	v_div_scale_f32 v53, vcc, 1.0, v49, 1.0
	v_mul_f32_e32 v54, v53, v51
	v_fma_f32 v55, -v50, v54, v53
	v_fmac_f32_e32 v54, v55, v51
	v_fma_f32 v50, -v50, v54, v53
	v_div_fmas_f32 v50, v50, v51, v54
	v_div_fixup_f32 v49, v50, v49, 1.0
	v_div_scale_f32 v50, s[28:29], v48, v48, 1.0
	v_rcp_f32_e32 v51, v50
	s_nop 0
	v_fma_f32 v53, -v50, v51, 1.0
	v_fmac_f32_e32 v51, v53, v51
	v_div_scale_f32 v53, vcc, 1.0, v48, 1.0
	v_mul_f32_e32 v54, v53, v51
	v_fma_f32 v55, -v50, v54, v53
	v_fmac_f32_e32 v54, v55, v51
	v_fma_f32 v50, -v50, v54, v53
	v_div_fmas_f32 v50, v50, v51, v54
	v_div_fixup_f32 v48, v50, v48, 1.0
	v_cvt_pk_bf16_f32 v48, v48, v49
	v_mov_b32_e32 v22, v52
	v_mov_b32_e32 v23, v48
	v_div_scale_f32 v48, s[28:29], v45, v45, 1.0
	v_rcp_f32_e32 v49, v48
	s_nop 0
	v_fma_f32 v50, -v48, v49, 1.0
	v_fmac_f32_e32 v49, v50, v49
	v_div_scale_f32 v50, vcc, 1.0, v45, 1.0
	v_mul_f32_e32 v51, v50, v49
	v_fma_f32 v52, -v48, v51, v50
	v_fmac_f32_e32 v51, v52, v49
	v_fma_f32 v48, -v48, v51, v50
	v_div_fmas_f32 v48, v48, v49, v51
	v_div_fixup_f32 v45, v48, v45, 1.0
	v_div_scale_f32 v48, s[28:29], v44, v44, 1.0
	v_rcp_f32_e32 v49, v48
	s_nop 0
	v_fma_f32 v50, -v48, v49, 1.0
	v_fmac_f32_e32 v49, v50, v49
	v_div_scale_f32 v50, vcc, 1.0, v44, 1.0
	v_mul_f32_e32 v51, v50, v49
	v_fma_f32 v52, -v48, v51, v50
	v_fmac_f32_e32 v51, v52, v49
	v_fma_f32 v48, -v48, v51, v50
	v_div_fmas_f32 v48, v48, v49, v51
	v_div_fixup_f32 v44, v48, v44, 1.0
	v_cvt_pk_bf16_f32 v48, v44, v45
	v_mul_f32_e32 v44, 0xbfb8aa3b, v46
	v_mul_f32_e32 v45, 0xbfb8aa3b, v47
	v_exp_f32_e32 v44, v44
	v_exp_f32_e32 v45, v45
	s_nop 0
	v_pk_add_f32 v[44:45], v[44:45], 1.0 op_sel_hi:[1,0]
	s_nop 0
	v_div_scale_f32 v46, s[28:29], v45, v45, 1.0
	v_rcp_f32_e32 v47, v46
	s_nop 0
	v_fma_f32 v49, -v46, v47, 1.0
	v_fmac_f32_e32 v47, v49, v47
	v_div_scale_f32 v49, vcc, 1.0, v45, 1.0
	v_mul_f32_e32 v50, v49, v47
	v_fma_f32 v51, -v46, v50, v49
	v_fmac_f32_e32 v50, v51, v47
	v_fma_f32 v46, -v46, v50, v49
	v_div_fmas_f32 v46, v46, v47, v50
	v_div_fixup_f32 v45, v46, v45, 1.0
	v_div_scale_f32 v46, s[28:29], v44, v44, 1.0
	v_rcp_f32_e32 v47, v46
	s_nop 0
	v_fma_f32 v49, -v46, v47, 1.0
	v_fmac_f32_e32 v47, v49, v47
	v_div_scale_f32 v49, vcc, 1.0, v44, 1.0
	v_mul_f32_e32 v50, v49, v47
	v_fma_f32 v51, -v46, v50, v49
	v_fmac_f32_e32 v50, v51, v47
	v_fma_f32 v46, -v46, v50, v49
	v_div_fmas_f32 v46, v46, v47, v50
	v_div_fixup_f32 v44, v46, v44, 1.0
	v_cvt_pk_bf16_f32 v44, v44, v45
	v_mov_b32_e32 v24, v48
	v_mov_b32_e32 v25, v44
	v_div_scale_f32 v44, s[28:29], v41, v41, 1.0
	v_rcp_f32_e32 v45, v44
	s_nop 0
	v_fma_f32 v46, -v44, v45, 1.0
	v_fmac_f32_e32 v45, v46, v45
	v_div_scale_f32 v46, vcc, 1.0, v41, 1.0
	v_mul_f32_e32 v47, v46, v45
	v_fma_f32 v48, -v44, v47, v46
	v_fmac_f32_e32 v47, v48, v45
	v_fma_f32 v44, -v44, v47, v46
	v_div_fmas_f32 v44, v44, v45, v47
	v_div_fixup_f32 v41, v44, v41, 1.0
	v_div_scale_f32 v44, s[28:29], v40, v40, 1.0
	v_rcp_f32_e32 v45, v44
	s_nop 0
	v_fma_f32 v46, -v44, v45, 1.0
	v_fmac_f32_e32 v45, v46, v45
	v_div_scale_f32 v46, vcc, 1.0, v40, 1.0
	v_mul_f32_e32 v47, v46, v45
	v_fma_f32 v48, -v44, v47, v46
	v_fmac_f32_e32 v47, v48, v45
	v_fma_f32 v44, -v44, v47, v46
	v_div_fmas_f32 v44, v44, v45, v47
	v_div_fixup_f32 v40, v44, v40, 1.0
	v_cvt_pk_bf16_f32 v44, v40, v41
	v_mul_f32_e32 v40, 0xbfb8aa3b, v42
	v_mul_f32_e32 v41, 0xbfb8aa3b, v43
	v_exp_f32_e32 v40, v40
	v_exp_f32_e32 v41, v41
	s_nop 0
	v_pk_add_f32 v[40:41], v[40:41], 1.0 op_sel_hi:[1,0]
	s_nop 0
	v_div_scale_f32 v42, s[28:29], v41, v41, 1.0
	v_rcp_f32_e32 v43, v42
	s_nop 0
	v_fma_f32 v45, -v42, v43, 1.0
	v_fmac_f32_e32 v43, v45, v43
	v_div_scale_f32 v45, vcc, 1.0, v41, 1.0
	v_mul_f32_e32 v46, v45, v43
	v_fma_f32 v47, -v42, v46, v45
	v_fmac_f32_e32 v46, v47, v43
	v_fma_f32 v42, -v42, v46, v45
	v_div_fmas_f32 v42, v42, v43, v46
	v_div_fixup_f32 v41, v42, v41, 1.0
	v_div_scale_f32 v42, s[28:29], v40, v40, 1.0
	v_rcp_f32_e32 v43, v42
	s_nop 0
	v_fma_f32 v45, -v42, v43, 1.0
	v_fmac_f32_e32 v43, v45, v43
	v_div_scale_f32 v45, vcc, 1.0, v40, 1.0
	v_mul_f32_e32 v46, v45, v43
	v_fma_f32 v47, -v42, v46, v45
	v_fmac_f32_e32 v46, v47, v43
	v_fma_f32 v42, -v42, v46, v45
	v_div_fmas_f32 v42, v42, v43, v46
	v_div_fixup_f32 v40, v42, v40, 1.0
	v_cvt_pk_bf16_f32 v40, v40, v41
	v_mov_b32_e32 v26, v44
	v_mov_b32_e32 v27, v40
	v_div_scale_f32 v40, s[28:29], v37, v37, 1.0
	v_rcp_f32_e32 v41, v40
	s_nop 0
	v_fma_f32 v42, -v40, v41, 1.0
	v_fmac_f32_e32 v41, v42, v41
	v_div_scale_f32 v42, vcc, 1.0, v37, 1.0
	v_mul_f32_e32 v43, v42, v41
	v_fma_f32 v44, -v40, v43, v42
	v_fmac_f32_e32 v43, v44, v41
	v_fma_f32 v40, -v40, v43, v42
	v_div_fmas_f32 v40, v40, v41, v43
	v_div_fixup_f32 v37, v40, v37, 1.0
	v_div_scale_f32 v40, s[28:29], v36, v36, 1.0
	v_rcp_f32_e32 v41, v40
	s_nop 0
	v_fma_f32 v42, -v40, v41, 1.0
	v_fmac_f32_e32 v41, v42, v41
	v_div_scale_f32 v42, vcc, 1.0, v36, 1.0
	v_mul_f32_e32 v43, v42, v41
	v_fma_f32 v44, -v40, v43, v42
	v_fmac_f32_e32 v43, v44, v41
	v_fma_f32 v40, -v40, v43, v42
	v_div_fmas_f32 v40, v40, v41, v43
	v_div_fixup_f32 v36, v40, v36, 1.0
	v_cvt_pk_bf16_f32 v40, v36, v37
	v_mul_f32_e32 v36, 0xbfb8aa3b, v38
	v_mul_f32_e32 v37, 0xbfb8aa3b, v39
	v_exp_f32_e32 v36, v36
	v_exp_f32_e32 v37, v37
	s_nop 0
	v_pk_add_f32 v[36:37], v[36:37], 1.0 op_sel_hi:[1,0]
	s_nop 0
	v_div_scale_f32 v38, s[28:29], v37, v37, 1.0
	v_rcp_f32_e32 v39, v38
	s_nop 0
	v_fma_f32 v41, -v38, v39, 1.0
	v_fmac_f32_e32 v39, v41, v39
	v_div_scale_f32 v41, vcc, 1.0, v37, 1.0
	v_mul_f32_e32 v42, v41, v39
	v_fma_f32 v43, -v38, v42, v41
	v_fmac_f32_e32 v42, v43, v39
	v_fma_f32 v38, -v38, v42, v41
	v_div_fmas_f32 v38, v38, v39, v42
	v_div_fixup_f32 v37, v38, v37, 1.0
	v_div_scale_f32 v38, s[28:29], v36, v36, 1.0
	v_rcp_f32_e32 v39, v38
	s_nop 0
	v_fma_f32 v41, -v38, v39, 1.0
	v_fmac_f32_e32 v39, v41, v39
	v_div_scale_f32 v41, vcc, 1.0, v36, 1.0
	v_mul_f32_e32 v42, v41, v39
	v_fma_f32 v43, -v38, v42, v41
	v_fmac_f32_e32 v42, v43, v39
	v_fma_f32 v38, -v38, v42, v41
	v_div_fmas_f32 v38, v38, v39, v42
	v_div_fixup_f32 v36, v38, v36, 1.0
	v_cvt_pk_bf16_f32 v36, v36, v37
	v_mov_b32_e32 v28, v40
	v_mov_b32_e32 v29, v36
	v_div_scale_f32 v36, s[28:29], v33, v33, 1.0
	v_rcp_f32_e32 v37, v36
	s_nop 0
	v_fma_f32 v38, -v36, v37, 1.0
	v_fmac_f32_e32 v37, v38, v37
	v_div_scale_f32 v38, vcc, 1.0, v33, 1.0
	v_mul_f32_e32 v39, v38, v37
	v_fma_f32 v40, -v36, v39, v38
	v_fmac_f32_e32 v39, v40, v37
	v_fma_f32 v36, -v36, v39, v38
	v_div_fmas_f32 v36, v36, v37, v39
	v_div_fixup_f32 v33, v36, v33, 1.0
	v_div_scale_f32 v36, s[28:29], v32, v32, 1.0
	v_rcp_f32_e32 v37, v36
	s_nop 0
	v_fma_f32 v38, -v36, v37, 1.0
	v_fmac_f32_e32 v37, v38, v37
	v_div_scale_f32 v38, vcc, 1.0, v32, 1.0
	v_mul_f32_e32 v39, v38, v37
	v_fma_f32 v40, -v36, v39, v38
	v_fmac_f32_e32 v39, v40, v37
	v_fma_f32 v36, -v36, v39, v38
	v_div_fmas_f32 v36, v36, v37, v39
	v_div_fixup_f32 v32, v36, v32, 1.0
	v_cvt_pk_bf16_f32 v36, v32, v33
	v_mul_f32_e32 v32, 0xbfb8aa3b, v34
	v_mul_f32_e32 v33, 0xbfb8aa3b, v35
	v_exp_f32_e32 v32, v32
	v_exp_f32_e32 v33, v33
	s_nop 0
	v_pk_add_f32 v[32:33], v[32:33], 1.0 op_sel_hi:[1,0]
	s_nop 0
	v_div_scale_f32 v34, s[28:29], v33, v33, 1.0
	v_rcp_f32_e32 v35, v34
	s_nop 0
	v_fma_f32 v37, -v34, v35, 1.0
	v_fmac_f32_e32 v35, v37, v35
	v_div_scale_f32 v37, vcc, 1.0, v33, 1.0
	v_mul_f32_e32 v38, v37, v35
	v_fma_f32 v39, -v34, v38, v37
	v_fmac_f32_e32 v38, v39, v35
	v_fma_f32 v34, -v34, v38, v37
	v_div_fmas_f32 v34, v34, v35, v38
	v_div_fixup_f32 v33, v34, v33, 1.0
	v_div_scale_f32 v34, s[28:29], v32, v32, 1.0
	v_rcp_f32_e32 v35, v34
	s_mov_b64 s[28:29], s[44:45]
	v_fma_f32 v37, -v34, v35, 1.0
	v_fmac_f32_e32 v35, v37, v35
	v_div_scale_f32 v37, vcc, 1.0, v32, 1.0
	v_mul_f32_e32 v38, v37, v35
	v_fma_f32 v39, -v34, v38, v37
	v_fmac_f32_e32 v38, v39, v35
	v_fma_f32 v34, -v34, v38, v37
	v_div_fmas_f32 v34, v34, v35, v38
	v_div_fixup_f32 v32, v34, v32, 1.0
	v_cvt_pk_bf16_f32 v32, v32, v33
	v_mov_b32_e32 v30, v36
	v_mov_b32_e32 v31, v32
	s_cbranch_scc1 .LBB0_93
	s_lshl_b32 s26, s40, 10
	s_addk_i32 s26, 0x400
	s_add_u32 s28, s26, s37
	s_addc_u32 s29, 0, s33
	v_readlane_b32 s0, v239, 18
	s_lshl_b64 s[28:29], s[28:29], 11
	v_readlane_b32 s8, v239, 26
	v_readlane_b32 s9, v239, 27
	s_add_u32 s28, s8, s28
	s_addc_u32 s29, s9, s29
	s_mov_b64 s[92:93], s[38:39]
	v_readlane_b32 s1, v239, 19
	v_readlane_b32 s2, v239, 20
	v_readlane_b32 s3, v239, 21
	v_readlane_b32 s4, v239, 22
	v_readlane_b32 s5, v239, 23
	v_readlane_b32 s6, v239, 24
	v_readlane_b32 s7, v239, 25
	v_readlane_b32 s10, v239, 28
	v_readlane_b32 s11, v239, 29
	v_readlane_b32 s12, v239, 30
	v_readlane_b32 s13, v239, 31
	v_readlane_b32 s14, v239, 32
	v_readlane_b32 s15, v239, 33

.LBB0_96:
	s_cmpk_gt_u32 s41, 0x1bf
	s_cselect_b64 s[84:85], -1, 0
	s_cmp_lg_u32 s41, 0
	s_cbranch_scc1 .Ld_step_2
	v_add_u32_e32 v160, v168, v166
	v_add_u32_e32 v243, v168, v169
	v_add_u32_e32 v241, v167, v166
	v_add_u32_e32 v242, v167, v169
	v_readfirstlane_b32 s100, v184
	s_lshl_b32 s100, s100, 4
	s_cmp_lg_u32 m0, -1
	s_cbranch_scc1 .Ld_step_2
	s_waitcnt vmcnt(0)
	ds_write_b128 v170, v[0:3]
	ds_write_b128 v170, v[4:7] offset:4096
	ds_write_b128 v170, v[8:11] offset:8192
	ds_write_b128 v170, v[12:15] offset:12288
	ds_write_b128 v170, v[16:19] offset:16384
	ds_write_b128 v170, v[20:23] offset:20480
	ds_write_b128 v170, v[24:27] offset:24576
	ds_write_b128 v170, v[28:31] offset:28672
	s_mov_b32 m0, 0
	s_waitcnt lgkmcnt(0)
	s_barrier
.Ld_step_2:
	s_cmpk_gt_u32 s41, 0x1bf
	s_cbranch_scc1 .Ld_last_2
	s_mov_b64 s[86:87], s[34:35]
	s_mov_b64 s[88:89], s[50:51]
	s_mov_b32 s90, 10
	s_mov_b32 s91, 0x8000
	s_add_i32 s98, s41, 64
	s_lshl_b32 s98, s98, 1
	s_branch .Ld_issue_2

.Ld_noissue_2:
	ds_read_b128 v[172:175], v160 offset:16384
	ds_read_b128 v[180:183], v241
	ds_read_b128 v[214:217], v160 offset:18432
	ds_read_b128 v[218:221], v160 offset:20480
	ds_read_b128 v[222:225], v160 offset:22528
	ds_read_b128 v[244:247], v241 offset:2048
	ds_read_b128 v[248:251], v241 offset:4096
	ds_read_b128 v[252:255], v241 offset:6144
	s_waitcnt lgkmcnt(6)
	v_mfma_f32_16x16x32_bf16 v[92:95], v[172:175], v[180:183], v[92:95]
	s_waitcnt lgkmcnt(5)
	v_mfma_f32_16x16x32_bf16 v[88:91], v[214:217], v[180:183], v[88:91]
	s_waitcnt lgkmcnt(4)
	v_mfma_f32_16x16x32_bf16 v[84:87], v[218:221], v[180:183], v[84:87]
	s_waitcnt lgkmcnt(3)
	v_mfma_f32_16x16x32_bf16 v[80:83], v[222:225], v[180:183], v[80:83]
	ds_read_b128 v[180:183], v242
	s_waitcnt lgkmcnt(3)
	v_mfma_f32_16x16x32_bf16 v[76:79], v[172:175], v[244:247], v[76:79]
	v_mfma_f32_16x16x32_bf16 v[72:75], v[214:217], v[244:247], v[72:75]
	v_mfma_f32_16x16x32_bf16 v[68:71], v[218:221], v[244:247], v[68:71]
	v_mfma_f32_16x16x32_bf16 v[64:67], v[222:225], v[244:247], v[64:67]
	ds_read_b128 v[244:247], v242 offset:2048
	s_waitcnt lgkmcnt(3)
	v_mfma_f32_16x16x32_bf16 v[60:63], v[172:175], v[248:251], v[60:63]
	s_waitcnt lgkmcnt(2)
	v_mfma_f32_16x16x32_bf16 v[44:47], v[172:175], v[252:255], v[44:47]
	ds_read_b128 v[172:175], v243 offset:16384
	v_mfma_f32_16x16x32_bf16 v[56:59], v[214:217], v[248:251], v[56:59]
	v_mfma_f32_16x16x32_bf16 v[40:43], v[214:217], v[252:255], v[40:43]
	ds_read_b128 v[214:217], v243 offset:18432
	v_mfma_f32_16x16x32_bf16 v[52:55], v[218:221], v[248:251], v[52:55]
	v_mfma_f32_16x16x32_bf16 v[32:35], v[218:221], v[252:255], v[32:35]
	ds_read_b128 v[218:221], v243 offset:20480
	v_mfma_f32_16x16x32_bf16 v[48:51], v[222:225], v[248:251], v[48:51]
	v_mfma_f32_16x16x32_bf16 v[36:39], v[222:225], v[252:255], v[36:39]
	ds_read_b128 v[222:225], v243 offset:22528
	ds_read_b128 v[248:251], v242 offset:4096
	ds_read_b128 v[252:255], v242 offset:6144
	s_waitcnt lgkmcnt(5)
	v_mfma_f32_16x16x32_bf16 v[92:95], v[172:175], v[180:183], v[92:95]
	v_mfma_f32_16x16x32_bf16 v[76:79], v[172:175], v[244:247], v[76:79]
	s_waitcnt lgkmcnt(4)
	v_mfma_f32_16x16x32_bf16 v[88:91], v[214:217], v[180:183], v[88:91]
	v_mfma_f32_16x16x32_bf16 v[72:75], v[214:217], v[244:247], v[72:75]
	s_waitcnt lgkmcnt(3)
	v_mfma_f32_16x16x32_bf16 v[84:87], v[218:221], v[180:183], v[84:87]
	v_mfma_f32_16x16x32_bf16 v[68:71], v[218:221], v[244:247], v[68:71]
	s_waitcnt lgkmcnt(2)
	v_mfma_f32_16x16x32_bf16 v[80:83], v[222:225], v[180:183], v[80:83]
	v_mfma_f32_16x16x32_bf16 v[64:67], v[222:225], v[244:247], v[64:67]
	s_waitcnt lgkmcnt(1)
	v_mfma_f32_16x16x32_bf16 v[60:63], v[172:175], v[248:251], v[60:63]
	v_mfma_f32_16x16x32_bf16 v[56:59], v[214:217], v[248:251], v[56:59]
	v_mfma_f32_16x16x32_bf16 v[52:55], v[218:221], v[248:251], v[52:55]
	v_mfma_f32_16x16x32_bf16 v[48:51], v[222:225], v[248:251], v[48:51]
	s_waitcnt vmcnt(0)
	s_waitcnt lgkmcnt(0)
	s_barrier
	v_mfma_f32_16x16x32_bf16 v[44:47], v[172:175], v[252:255], v[44:47]
	v_mfma_f32_16x16x32_bf16 v[40:43], v[214:217], v[252:255], v[40:43]
	v_mfma_f32_16x16x32_bf16 v[32:35], v[218:221], v[252:255], v[32:35]
	v_mfma_f32_16x16x32_bf16 v[36:39], v[222:225], v[252:255], v[36:39]
	v_xor_b32_e32 v160, 0x8000, v160
	v_xor_b32_e32 v243, 0x8000, v243
	v_xor_b32_e32 v241, 0x8000, v241
	v_xor_b32_e32 v242, 0x8000, v242
	s_add_i32 s41, s41, 64
	s_andn2_b64 vcc, exec, s[84:85]
	s_cbranch_vccz .LBB0_80
	s_branch .LBB0_96
